# swizzled bf16 latent cache layout (coalesced latent loads in fused sample attention)
# baseline (speedup 1.0000x reference)
; DEVI u32x4 pack8(const f32x4 a, const f32x4 b) { u32x4 w; w.x = cvtpk(a[0], a[1]); w.y = cvtpk(a[2], a[3]); w.z = cvtpk(b[0], b[1]); w.w = cvtpk(b[2], b[3]); return w; }
; DEVI const float* IN(int i) { return *(const float* const __attribute__((address_space(4)))*)(kargs() + 8 * i); }
; DEVI void prologue(int wv, LAS unsigned char* lds) {
;     ...
;         const float* cache_ckv = IN(2); bf16_t* ckvb = (bf16_t*)(ws + O_CKVB);
;         for (size_t i = gt; i < (size_t)2 * MC * 256 / 8; i += 8 * NGT) {
;             f32x4 a[8], b[8];
; #pragma unroll
;             for (int k = 0; k < 8; ++k) { const size_t ii = i + k * NGT; if (ii < (size_t)2 * MC * 256 / 8) { a[k] = *(const f32x4*)(cache_ckv + ii * 8); b[k] = *(const f32x4*)(cache_ckv + ii * 8 + 4); } }
; #pragma unroll
;             for (int k = 0; k < 8; ++k) { const size_t ii = i + k * NGT; if (ii < (size_t)2 * MC * 256 / 8) *(u32x4*)(ckvb + ii * 8) = pack8(a[k], b[k]); }
;         }
;     }
.LBB0_359:
	s_mov_b64 s[24:25], 0x800000
	s_mov_b64 s[2:3], s[0:1]
	v_cmp_gt_u64_e32 vcc, s[24:25], v[68:69]
	s_and_saveexec_b64 s[26:27], vcc
	s_cbranch_execz .LBB0_390
	s_load_dwordx2 s[28:29], s[2:3], 0x10
	s_lshl_b64 s[2:3], s[18:19], 13
	v_lshl_add_u64 v[0:1], v[64:65], 4, s[2:3]
	s_mov_b64 s[2:3], 0x3bb0800
	v_lshl_add_u64 v[66:67], v[0:1], 0, s[2:3]
	s_lshl_b64 s[2:3], s[18:19], 14
	v_lshlrev_b64 v[0:1], 5, v[64:65]
	s_lshl_b64 s[30:31], s[16:17], 16
	v_lshl_add_u64 v[70:71], s[2:3], 0, v[0:1]
	s_lshl_b64 s[34:35], s[16:17], 17
	s_lshl_b64 s[2:3], s[16:17], 10
	s_add_u32 s2, s2, s6
	s_addc_u32 s3, s3, s7
	v_lshl_add_u64 v[0:1], s[2:3], 0, v[64:65]
	s_add_u32 s2, s6, s22
	s_addc_u32 s3, s7, s23
	v_lshl_add_u64 v[76:77], s[2:3], 0, v[64:65]
	s_lshl_b64 s[36:37], s[16:17], 12
	s_mul_i32 s2, s16, 0x600
	s_mul_hi_i32 s3, s16, 0x600
	s_add_u32 s2, s2, s6
	v_mov_b64_e32 v[2:3], 0x3bb0800
	s_addc_u32 s3, s3, s7
	v_lshlrev_b64 v[72:73], 5, v[0:1]
	v_lshl_add_u64 v[74:75], v[0:1], 4, v[2:3]
	v_lshl_add_u64 v[0:1], s[2:3], 0, v[64:65]
	s_lshl_b64 s[2:3], s[16:17], 11
	s_add_u32 s2, s2, s6
	s_addc_u32 s3, s3, s7
	v_lshlrev_b64 v[78:79], 5, v[0:1]
	v_lshl_add_u64 v[80:81], v[0:1], 4, v[2:3]
	v_lshl_add_u64 v[0:1], s[2:3], 0, v[64:65]
	s_mul_i32 s2, s16, 0xa00
	s_mul_hi_i32 s3, s16, 0xa00
	s_add_u32 s2, s2, s6
	s_addc_u32 s3, s3, s7
	v_lshlrev_b64 v[84:85], 5, v[0:1]
	v_lshl_add_u64 v[86:87], v[0:1], 4, v[2:3]
	v_lshl_add_u64 v[0:1], s[2:3], 0, v[64:65]
	s_mul_i32 s2, s16, 0xe00
	s_mul_hi_i32 s3, s16, 0xe00
	s_add_u32 s2, s2, s6
	s_addc_u32 s3, s3, s7
	v_lshlrev_b64 v[90:91], 5, v[0:1]
	v_lshl_add_u64 v[92:93], v[0:1], 4, v[2:3]
	v_lshl_add_u64 v[0:1], s[2:3], 0, v[64:65]
	s_mul_i32 s2, s16, 0xc00
	s_mul_hi_i32 s3, s16, 0xc00
	s_add_u32 s2, s2, s6
	s_addc_u32 s3, s3, s7
	v_lshl_add_u64 v[4:5], s[2:3], 0, v[64:65]
	v_lshlrev_b64 v[96:97], 5, v[4:5]
	v_lshlrev_b64 v[100:101], 5, v[0:1]
	v_or_b32_e32 v72, 16, v72
	v_or_b32_e32 v78, 16, v78
	v_lshlrev_b64 v[82:83], 5, v[76:77]
	v_or_b32_e32 v84, 16, v84
	v_lshl_add_u64 v[88:89], v[76:77], 4, v[2:3]
	v_or_b32_e32 v90, 16, v90
	v_lshl_add_u64 v[94:95], v[0:1], 4, v[2:3]
	v_or_b32_e32 v96, 16, v96
	v_lshl_add_u64 v[98:99], v[4:5], 4, v[2:3]
	v_or_b32_e32 v100, 16, v100
	v_bfe_u32 v0, v70, 5, 10
	v_and_b32_e32 v70, 0xffff801f, v70
	v_and_b32_e32 v2, 31, v0
	v_lshl_or_b32 v70, v2, 10, v70
	v_lshrrev_b32_e32 v2, 8, v0
	v_lshl_or_b32 v70, v2, 8, v70
	v_bfe_u32 v2, v0, 5, 1
	v_lshl_or_b32 v70, v2, 7, v70
	v_bfe_u32 v2, v0, 6, 2
	v_lshl_or_b32 v70, v2, 5, v70
	v_bfe_u32 v0, v82, 5, 10
	v_and_b32_e32 v82, 0xffff801f, v82
	v_and_b32_e32 v2, 31, v0
	v_lshl_or_b32 v82, v2, 10, v82
	v_lshrrev_b32_e32 v2, 8, v0
	v_lshl_or_b32 v82, v2, 8, v82
	v_bfe_u32 v2, v0, 5, 1
	v_lshl_or_b32 v82, v2, 7, v82
	v_bfe_u32 v2, v0, 6, 2
	v_lshl_or_b32 v82, v2, 5, v82
	v_bfe_u32 v0, v72, 5, 10
	v_and_b32_e32 v72, 0xffff801f, v72
	v_and_b32_e32 v2, 31, v0
	v_lshl_or_b32 v72, v2, 10, v72
	v_lshrrev_b32_e32 v2, 8, v0
	v_lshl_or_b32 v72, v2, 8, v72
	v_bfe_u32 v2, v0, 5, 1
	v_lshl_or_b32 v72, v2, 7, v72
	v_bfe_u32 v2, v0, 6, 2
	v_lshl_or_b32 v72, v2, 5, v72
	v_bfe_u32 v0, v78, 5, 10
	v_and_b32_e32 v78, 0xffff801f, v78
	v_and_b32_e32 v2, 31, v0
	v_lshl_or_b32 v78, v2, 10, v78
	v_lshrrev_b32_e32 v2, 8, v0
	v_lshl_or_b32 v78, v2, 8, v78
	v_bfe_u32 v2, v0, 5, 1
	v_lshl_or_b32 v78, v2, 7, v78
	v_bfe_u32 v2, v0, 6, 2
	v_lshl_or_b32 v78, v2, 5, v78
	v_bfe_u32 v0, v84, 5, 10
	v_and_b32_e32 v84, 0xffff801f, v84
	v_and_b32_e32 v2, 31, v0
	v_lshl_or_b32 v84, v2, 10, v84
	v_lshrrev_b32_e32 v2, 8, v0
	v_lshl_or_b32 v84, v2, 8, v84
	v_bfe_u32 v2, v0, 5, 1
	v_lshl_or_b32 v84, v2, 7, v84
	v_bfe_u32 v2, v0, 6, 2
	v_lshl_or_b32 v84, v2, 5, v84
	v_bfe_u32 v0, v90, 5, 10
	v_and_b32_e32 v90, 0xffff801f, v90
	v_and_b32_e32 v2, 31, v0
	v_lshl_or_b32 v90, v2, 10, v90
	v_lshrrev_b32_e32 v2, 8, v0
	v_lshl_or_b32 v90, v2, 8, v90
	v_bfe_u32 v2, v0, 5, 1
	v_lshl_or_b32 v90, v2, 7, v90
	v_bfe_u32 v2, v0, 6, 2
	v_lshl_or_b32 v90, v2, 5, v90
	v_bfe_u32 v0, v96, 5, 10
	v_and_b32_e32 v96, 0xffff801f, v96
	v_and_b32_e32 v2, 31, v0
	v_lshl_or_b32 v96, v2, 10, v96
	v_lshrrev_b32_e32 v2, 8, v0
	v_lshl_or_b32 v96, v2, 8, v96
	v_bfe_u32 v2, v0, 5, 1
	v_lshl_or_b32 v96, v2, 7, v96
	v_bfe_u32 v2, v0, 6, 2
	v_lshl_or_b32 v96, v2, 5, v96
	v_bfe_u32 v0, v100, 5, 10
	v_and_b32_e32 v100, 0xffff801f, v100
	v_and_b32_e32 v2, 31, v0
	v_lshl_or_b32 v100, v2, 10, v100
	v_lshrrev_b32_e32 v2, 8, v0
	v_lshl_or_b32 v100, v2, 8, v100
	v_bfe_u32 v2, v0, 5, 1
	v_lshl_or_b32 v100, v2, 7, v100
	v_bfe_u32 v2, v0, 6, 2
	v_lshl_or_b32 v100, v2, 5, v100
	s_mov_b64 s[38:39], 0
	s_mov_b64 s[40:41], 0x7fffff
	s_waitcnt lgkmcnt(0)
	s_mov_b64 s[42:43], s[20:21]
	s_branch .LBB0_362

; #define TID() tid_now(wv)
; #define BID() opq_s((int)blockIdx.x)
; #define GDIM() opq_s((int)gridDim.x)
; DEVI unsigned cvtpk(float lo, float hi) { f32x2_t v = {lo, hi}; bf16x2_t b = __builtin_convertvector(v, bf16x2_t); return __builtin_bit_cast(unsigned, b); }
; DEVI float bflo(unsigned w) { return __uint_as_float(w << 16); }
; DEVI float bfhi(unsigned w) { return __uint_as_float(w & 0xffff0000u); }
; DEVI const float* IN(int i) { return *(const float* const __attribute__((address_space(4)))*)(kargs() + 8 * i); }
; DEVI float* OUTP() { return *(float* const __attribute__((address_space(4)))*)(kargs() + 8 * 21); }
; DEVI void thin_rows(int wv, int l) {
;     const int tid = TID(), lane = tid & 63, wave = __builtin_amdgcn_readfirstlane(tid >> 6);
;     const int gw = BID() * 8 + wave, NGW = GDIM() * 8;
;     unsigned char* ws = WSP(); float* out = OUTP();
;     const float* gkva = IN(8) + l * 256;
;     const float* sp = IN(4) + (size_t)l * 32 * 15 * 512;
;     const float* ssq_zkv = (const float*)(ws + O_SSQZ) + (size_t)(5 + l) * MT;
;     const bf16_t* zkv = (const bf16_t*)(ws + O_ZKV); const bf16_t* pp = (const bf16_t*)(ws + O_PP); bf16_t* pooled = (bf16_t*)(ws + O_POOLED);
;     float* ockv_p = out + OUT_CKVP + (size_t)l * MP * 256; float* ockv_s = out + OUT_CKVS + (size_t)l * MS * 256;
;     for (int c = gw; c < MT / 16; c += NGW) {
;         const int r0 = c * 16; const bool samp = r0 >= MP;
;         {
;             u32x2 z[16]; float sq[16];
; #pragma unroll
;             for (int i = 0; i < 16; ++i) { z[i] = *(const u32x2*)(zkv + (size_t)(r0 + i) * 256 + 4 * lane); sq[i] = ssq_zkv[r0 + i]; }
;             const f32x4 g = *(const f32x4*)(gkva + 4 * lane);
;             float* d0 = samp ? ockv_s + (size_t)(r0 - MP) * 256 : ockv_p + (size_t)r0 * 256;
; #pragma unroll
;             for (int i = 0; i < 16; ++i) {
;                 const float r = rsqrtf(sq[i] * (1.f / 256.f) + EPSF);
;                 f32x4 v = {bflo(z[i].x), bfhi(z[i].x), bflo(z[i].y), bfhi(z[i].y)}; v = v * r * g;
;                 __builtin_nontemporal_store(v, (f32x4*)(d0 + (size_t)i * 256 + 4 * lane));
;                 if (samp) { u32x2 o; o.x = cvtpk(v[0], v[1]); o.y = cvtpk(v[2], v[3]); *(u32x2*)((bf16_t*)(ws + O_CKVN) + (size_t)(r0 - MP + i) * 256 + 4 * lane) = o; }
;             }
;         }
.LBB0_977:
	v_mbcnt_lo_u32_b32 v2, -1, 0
	v_mbcnt_hi_u32_b32 v2, -1, v2
	v_lshl_or_b32 v2, s33, 6, v2
	s_mov_b32 s11, s95
	v_readfirstlane_b32 s2, v2
	s_ashr_i32 s10, s2, 6
	s_lshl_b32 s2, s11, 3
	s_add_i32 s43, s2, s10
	s_mov_b32 s26, s85
	s_mov_b64 s[4:5], s[0:1]
	s_mov_b64 s[6:7], s[0:1]
	s_mov_b64 s[8:9], s[0:1]
	s_mov_b64 s[2:3], s[0:1]
	s_cmpk_gt_i32 s43, 0x81f
	s_mov_b32 s47, s13
	s_cbranch_scc1 .LBB0_1230
	s_load_dwordx2 s[4:5], s[4:5], 0xb0
	s_nop 0
	s_load_dwordx2 s[6:7], s[6:7], 0xa8
	s_nop 0
	s_load_dwordx2 s[8:9], s[8:9], 0x40
	s_mul_i32 s12, s46, 0x8200
	s_lshl_b32 s49, s26, 3
	s_lshl_b64 s[50:51], s[12:13], 2
	s_waitcnt lgkmcnt(0)
	s_add_u32 s12, s4, s50
	s_addc_u32 s15, s5, s51
	s_add_u32 s48, s12, 0x147800
	s_addc_u32 s42, s15, 0
	s_lshl_b64 s[50:51], s[46:47], 25
	s_add_u32 s12, s6, s50
	s_addc_u32 s15, s7, s51
	s_add_u32 s38, s12, 0x8200000
	s_addc_u32 s96, s15, 0
	s_lshl_b64 s[50:51], s[46:47], 19
	s_load_dwordx2 s[2:3], s[2:3], 0x20
	s_add_u32 s6, s6, s50
	s_addc_u32 s7, s7, s51
	s_add_u32 s36, s6, 0xca78000
	s_addc_u32 s15, s7, 0
	s_mul_i32 s6, s46, 0xf0000
	s_waitcnt lgkmcnt(0)
	s_add_u32 s2, s2, s6
	s_addc_u32 s3, s3, 0
	s_lshl_b32 s12, s46, 8
	s_lshl_b64 s[6:7], s[12:13], 2
	v_and_b32_e32 v5, 63, v2
	s_add_u32 s6, s8, s6
	v_lshlrev_b32_e32 v0, 3, v5
	s_addc_u32 s7, s9, s7
	v_lshl_add_u64 v[6:7], s[4:5], 0, v[0:1]
	s_mov_b64 s[8:9], 0x11510800
	v_lshlrev_b32_e32 v0, 4, v5
	v_lshl_add_u64 v[150:151], v[6:7], 0, s[8:9]
	v_lshl_add_u64 v[152:153], s[6:7], 0, v[0:1]
	v_bfe_u32 v170, v2, 4, 2
	v_lshl_add_u64 v[2:3], s[4:5], 0, v[0:1]
	v_lshlrev_b32_e32 v0, 5, v5
	s_lshl_b32 s8, s11, 7
	s_lshl_b32 s9, s10, 4
	s_mov_b64 s[52:53], 0x12550800
	v_lshlrev_b32_e32 v4, 2, v5
	s_mov_b64 s[6:7], 0x3ce90800
	v_lshl_add_u64 v[158:159], s[2:3], 0, v[0:1]
	s_mov_b64 s[2:3], 0x1c7d0800
	s_add_i32 s8, s8, s9
	s_movk_i32 s30, 0x1000
	v_lshl_add_u64 v[154:155], v[6:7], 0, s[6:7]
	v_lshrrev_b32_e32 v6, 4, v5
	v_lshlrev_b32_e32 v6, 12, v6
	v_bfe_u32 v7, v5, 1, 2
	v_lshl_or_b32 v6, v7, 10, v6
	v_bfe_u32 v7, v5, 3, 1
	v_lshl_or_b32 v6, v7, 8, v6
	v_and_b32_e32 v7, 1, v5
	v_lshl_or_b32 v6, v7, 3, v6
	v_mov_b32_e32 v7, 0
	v_lshl_add_u64 v[6:7], s[4:5], 0, v[6:7]
	v_lshl_add_u64 v[154:155], v[6:7], 0, s[6:7]
	v_lshlrev_b32_e64 v171, v170, 2
	v_lshl_add_u64 v[156:157], v[2:3], 0, s[52:53]
	v_lshl_add_u64 v[160:161], v[2:3], 0, s[2:3]
	v_cmp_lt_u32_e64 s[2:3], 15, v5
	v_cmp_lt_u32_e64 s[4:5], 31, v5
	v_cmp_eq_u32_e64 s[6:7], 3, v170
	s_add_i32 s12, s8, 0xffff8000
	s_lshl_b32 s26, s26, 7
	v_lshlrev_b32_e32 v0, 2, v4
	s_branch .LBB0_981

; DEVI unsigned cvtpk(float lo, float hi) { f32x2_t v = {lo, hi}; bf16x2_t b = __builtin_convertvector(v, bf16x2_t); return __builtin_bit_cast(unsigned, b); }
; DEVI float bflo(unsigned w) { return __uint_as_float(w << 16); }
; DEVI float bfhi(unsigned w) { return __uint_as_float(w & 0xffff0000u); }
; DEVI void thin_rows(int wv, int l) {
;     ...
; #pragma unroll
;             for (int i = 0; i < 16; ++i) {
;                 const float r = rsqrtf(sq[i] * (1.f / 256.f) + EPSF);
;                 f32x4 v = {bflo(z[i].x), bfhi(z[i].x), bflo(z[i].y), bfhi(z[i].y)}; v = v * r * g;
;                 __builtin_nontemporal_store(v, (f32x4*)(d0 + (size_t)i * 256 + 4 * lane));
;                 if (samp) { u32x2 o; o.x = cvtpk(v[0], v[1]); o.y = cvtpk(v[2], v[3]); *(u32x2*)((bf16_t*)(ws + O_CKVN) + (size_t)(r0 - MP + i) * 256 + 4 * lane) = o; }
;             }
.LBB0_985:
	s_waitcnt vmcnt(16)
	v_fmamk_f32 v18, v18, 0x3b800000, v233
	v_mul_f32_e32 v24, 0x4b800000, v18
	v_cmp_gt_f32_e32 vcc, s25, v18
	v_and_b32_e32 v25, 0xffff0000, v22
	s_nop 0
	v_cndmask_b32_e32 v18, v18, v24, vcc
	v_rsq_f32_e32 v18, v18
	v_lshlrev_b32_e32 v24, 16, v22
	v_mul_f32_e32 v22, 0x45800000, v18
	v_cndmask_b32_e32 v18, v18, v22, vcc
	v_lshlrev_b32_e32 v22, 16, v23
	v_and_b32_e32 v23, 0xffff0000, v23
	v_pk_mul_f32 v[32:33], v[18:19], v[24:25] op_sel_hi:[0,1]
	v_pk_mul_f32 v[22:23], v[18:19], v[22:23] op_sel_hi:[0,1]
	s_waitcnt vmcnt(0)
	v_pk_mul_f32 v[24:25], v[22:23], v[8:9]
	v_pk_mul_f32 v[22:23], v[32:33], v[6:7]
	s_and_b64 vcc, exec, s[8:9]
	global_store_dwordx4 v0, v[22:25], s[10:11] nt
	s_cbranch_vccz .LBB0_987
	s_lshr_b32 s84, s12, 5
	s_lshl_b32 s84, s84, 14
	s_bfe_u32 s85, s12, 0x10004
	s_lshl_b32 s85, s85, 9
	s_add_i32 s84, s84, s85
	s_mov_b32 s85, 0
	v_cvt_pk_bf16_f32 v22, v22, v23
	v_cvt_pk_bf16_f32 v23, v24, v25
	v_lshl_add_u64 v[24:25], v[154:155], 0, s[84:85]
	global_store_dwordx2 v[24:25], v[22:23], off
.LBB0_987:
	v_fmamk_f32 v18, v19, 0x3b800000, v233
	v_cmp_gt_f32_e32 vcc, s25, v18
	v_mul_f32_e32 v19, 0x4b800000, v18
	v_lshlrev_b32_e32 v22, 16, v56
	v_cndmask_b32_e32 v18, v18, v19, vcc
	v_rsq_f32_e32 v18, v18
	v_and_b32_e32 v23, 0xffff0000, v56
	v_lshlrev_b32_e32 v24, 16, v57
	v_and_b32_e32 v25, 0xffff0000, v57
	v_mul_f32_e32 v19, 0x45800000, v18
	v_cndmask_b32_e32 v18, v18, v19, vcc
	v_pk_mul_f32 v[22:23], v[18:19], v[22:23] op_sel_hi:[0,1]
	v_pk_mul_f32 v[18:19], v[18:19], v[24:25] op_sel_hi:[0,1]
	v_pk_mul_f32 v[24:25], v[18:19], v[8:9]
	v_cndmask_b32_e64 v18, 0, 1, s[8:9]
	v_lshl_add_u64 v[32:33], s[10:11], 0, v[0:1]
	v_pk_mul_f32 v[22:23], v[22:23], v[6:7]
	v_cmp_ne_u32_e64 s[10:11], 1, v18
	s_andn2_b64 vcc, exec, s[8:9]
	global_store_dwordx4 v[32:33], v[22:25], off offset:1024 nt
	s_cbranch_vccnz .LBB0_989
	s_lshr_b32 s84, s12, 5
	s_lshl_b32 s84, s84, 14
	s_bfe_u32 s85, s12, 0x10004
	s_lshl_b32 s85, s85, 9
	s_add_i32 s84, s84, s85
	s_add_i32 s84, s84, 16
	s_mov_b32 s85, 0
	v_cvt_pk_bf16_f32 v18, v22, v23
	v_cvt_pk_bf16_f32 v19, v24, v25
	v_lshl_add_u64 v[22:23], v[154:155], 0, s[84:85]
	global_store_dwordx2 v[22:23], v[18:19], off
.LBB0_989:
	v_fmamk_f32 v18, v20, 0x3b800000, v233
	v_mul_f32_e32 v19, 0x4b800000, v18
	v_cmp_gt_f32_e32 vcc, s25, v18
	v_and_b32_e32 v23, 0xffff0000, v55
	s_nop 0
	v_cndmask_b32_e32 v18, v18, v19, vcc
	v_rsq_f32_e32 v20, v18
	v_lshlrev_b32_e32 v18, 16, v54
	v_and_b32_e32 v19, 0xffff0000, v54
	v_mul_f32_e32 v22, 0x45800000, v20
	v_cndmask_b32_e32 v20, v20, v22, vcc
	v_lshlrev_b32_e32 v22, 16, v55
	v_pk_mul_f32 v[18:19], v[20:21], v[18:19] op_sel_hi:[0,1]
	v_pk_mul_f32 v[22:23], v[20:21], v[22:23] op_sel_hi:[0,1]
	v_pk_mul_f32 v[24:25], v[22:23], v[8:9]
	v_pk_mul_f32 v[22:23], v[18:19], v[6:7]
	s_and_b64 vcc, exec, s[10:11]
	global_store_dwordx4 v[32:33], v[22:25], off offset:2048 nt
	s_cbranch_vccnz .LBB0_991
	s_lshr_b32 s84, s12, 5
	s_lshl_b32 s84, s84, 14
	s_bfe_u32 s85, s12, 0x10004
	s_lshl_b32 s85, s85, 9
	s_add_i32 s84, s84, s85
	s_add_i32 s84, s84, 32
	s_mov_b32 s85, 0
	v_cvt_pk_bf16_f32 v18, v22, v23
	v_cvt_pk_bf16_f32 v19, v24, v25
	v_lshl_add_u64 v[22:23], v[154:155], 0, s[84:85]
	global_store_dwordx2 v[22:23], v[18:19], off
.LBB0_991:
	v_fmamk_f32 v18, v21, 0x3b800000, v233
	v_mul_f32_e32 v19, 0x4b800000, v18
	v_cmp_gt_f32_e32 vcc, s25, v18
	v_lshlrev_b32_e32 v22, 16, v53
	v_and_b32_e32 v23, 0xffff0000, v53
	v_cndmask_b32_e32 v18, v18, v19, vcc
	v_rsq_f32_e32 v20, v18
	v_lshlrev_b32_e32 v18, 16, v52
	v_and_b32_e32 v19, 0xffff0000, v52
	v_mul_f32_e32 v21, 0x45800000, v20
	v_cndmask_b32_e32 v20, v20, v21, vcc
	v_pk_mul_f32 v[18:19], v[20:21], v[18:19] op_sel_hi:[0,1]
	v_pk_mul_f32 v[20:21], v[20:21], v[22:23] op_sel_hi:[0,1]
	v_pk_mul_f32 v[20:21], v[20:21], v[8:9]
	v_pk_mul_f32 v[18:19], v[18:19], v[6:7]
	s_and_b64 vcc, exec, s[10:11]
	global_store_dwordx4 v[32:33], v[18:21], off offset:3072 nt
	s_cbranch_vccnz .LBB0_993
	s_lshr_b32 s84, s12, 5
	s_lshl_b32 s84, s84, 14
	s_bfe_u32 s85, s12, 0x10004
	s_lshl_b32 s85, s85, 9
	s_add_i32 s84, s84, s85
	s_add_i32 s84, s84, 48
	s_mov_b32 s85, 0
	v_cvt_pk_bf16_f32 v18, v18, v19
	v_cvt_pk_bf16_f32 v19, v20, v21
	v_lshl_add_u64 v[20:21], v[154:155], 0, s[84:85]
	global_store_dwordx2 v[20:21], v[18:19], off
.LBB0_993:
	v_fmamk_f32 v14, v14, 0x3b800000, v233
	v_mul_f32_e32 v18, 0x4b800000, v14
	v_cmp_gt_f32_e32 vcc, s25, v14
	v_and_b32_e32 v19, 0xffff0000, v50
	v_and_b32_e32 v21, 0xffff0000, v51
	v_cndmask_b32_e32 v14, v14, v18, vcc
	v_rsq_f32_e32 v14, v14
	v_lshlrev_b32_e32 v18, 16, v50
	v_mul_f32_e32 v20, 0x45800000, v14
	v_cndmask_b32_e32 v14, v14, v20, vcc
	v_lshlrev_b32_e32 v20, 16, v51
	v_add_co_u32_e32 v22, vcc, 0x1000, v32
	v_pk_mul_f32 v[18:19], v[14:15], v[18:19] op_sel_hi:[0,1]
	v_pk_mul_f32 v[20:21], v[14:15], v[20:21] op_sel_hi:[0,1]
	v_addc_co_u32_e32 v23, vcc, 0, v33, vcc
	v_pk_mul_f32 v[20:21], v[20:21], v[8:9]
	v_pk_mul_f32 v[18:19], v[18:19], v[6:7]
	s_and_b64 vcc, exec, s[10:11]
	global_store_dwordx4 v[22:23], v[18:21], off nt
	s_cbranch_vccnz .LBB0_995
	s_lshr_b32 s84, s12, 5
	s_lshl_b32 s84, s84, 14
	s_bfe_u32 s85, s12, 0x10004
	s_lshl_b32 s85, s85, 9
	s_add_i32 s84, s84, s85
	s_add_i32 s84, s84, 64
	s_mov_b32 s85, 0
	v_cvt_pk_bf16_f32 v18, v18, v19
	v_cvt_pk_bf16_f32 v19, v20, v21
	v_lshl_add_u64 v[20:21], v[154:155], 0, s[84:85]
	global_store_dwordx2 v[20:21], v[18:19], off
; DEVI unsigned cvtpk(float lo, float hi) { f32x2_t v = {lo, hi}; bf16x2_t b = __builtin_convertvector(v, bf16x2_t); return __builtin_bit_cast(unsigned, b); }
; DEVI float bflo(unsigned w) { return __uint_as_float(w << 16); }
; DEVI float bfhi(unsigned w) { return __uint_as_float(w & 0xffff0000u); }
; DEVI void thin_rows(int wv, int l) {
;     ...
; #pragma unroll
;             for (int i = 0; i < 16; ++i) {
;                 const float r = rsqrtf(sq[i] * (1.f / 256.f) + EPSF);
;                 f32x4 v = {bflo(z[i].x), bfhi(z[i].x), bflo(z[i].y), bfhi(z[i].y)}; v = v * r * g;
;                 __builtin_nontemporal_store(v, (f32x4*)(d0 + (size_t)i * 256 + 4 * lane));
;                 if (samp) { u32x2 o; o.x = cvtpk(v[0], v[1]); o.y = cvtpk(v[2], v[3]); *(u32x2*)((bf16_t*)(ws + O_CKVN) + (size_t)(r0 - MP + i) * 256 + 4 * lane) = o; }
;             }
.LBB0_995:
	v_fmamk_f32 v14, v15, 0x3b800000, v233
	v_mul_f32_e32 v15, 0x4b800000, v14
	v_cmp_gt_f32_e32 vcc, s25, v14
	v_lshlrev_b32_e32 v20, 16, v49
	v_and_b32_e32 v21, 0xffff0000, v49
	v_cndmask_b32_e32 v14, v14, v15, vcc
	v_rsq_f32_e32 v18, v14
	v_lshlrev_b32_e32 v14, 16, v48
	v_and_b32_e32 v15, 0xffff0000, v48
	v_mul_f32_e32 v19, 0x45800000, v18
	v_cndmask_b32_e32 v18, v18, v19, vcc
	v_pk_mul_f32 v[14:15], v[18:19], v[14:15] op_sel_hi:[0,1]
	v_pk_mul_f32 v[18:19], v[18:19], v[20:21] op_sel_hi:[0,1]
	v_pk_mul_f32 v[20:21], v[18:19], v[8:9]
	v_pk_mul_f32 v[18:19], v[14:15], v[6:7]
	v_add_co_u32_e32 v14, vcc, 0x1000, v32
	s_nop 1
	v_addc_co_u32_e32 v15, vcc, 0, v33, vcc
	s_and_b64 vcc, exec, s[10:11]
	global_store_dwordx4 v[14:15], v[18:21], off offset:1024 nt
	s_cbranch_vccnz .LBB0_997
	s_lshr_b32 s84, s12, 5
	s_lshl_b32 s84, s84, 14
	s_bfe_u32 s85, s12, 0x10004
	s_lshl_b32 s85, s85, 9
	s_add_i32 s84, s84, s85
	s_add_i32 s84, s84, 80
	s_mov_b32 s85, 0
	v_cvt_pk_bf16_f32 v14, v18, v19
	v_cvt_pk_bf16_f32 v15, v20, v21
	v_lshl_add_u64 v[18:19], v[154:155], 0, s[84:85]
	global_store_dwordx2 v[18:19], v[14:15], off
.LBB0_997:
	v_fmamk_f32 v14, v16, 0x3b800000, v233
	v_mul_f32_e32 v15, 0x4b800000, v14
	v_cmp_gt_f32_e32 vcc, s25, v14
	v_and_b32_e32 v19, 0xffff0000, v47
	s_nop 0
	v_cndmask_b32_e32 v14, v14, v15, vcc
	v_rsq_f32_e32 v16, v14
	v_lshlrev_b32_e32 v14, 16, v46
	v_and_b32_e32 v15, 0xffff0000, v46
	v_mul_f32_e32 v18, 0x45800000, v16
	v_cndmask_b32_e32 v16, v16, v18, vcc
	v_lshlrev_b32_e32 v18, 16, v47
	v_pk_mul_f32 v[14:15], v[16:17], v[14:15] op_sel_hi:[0,1]
	v_pk_mul_f32 v[18:19], v[16:17], v[18:19] op_sel_hi:[0,1]
	v_pk_mul_f32 v[20:21], v[18:19], v[8:9]
	v_pk_mul_f32 v[18:19], v[14:15], v[6:7]
	v_add_co_u32_e32 v14, vcc, 0x1000, v32
	s_nop 1
	v_addc_co_u32_e32 v15, vcc, 0, v33, vcc
	s_and_b64 vcc, exec, s[10:11]
	global_store_dwordx4 v[14:15], v[18:21], off offset:2048 nt
	s_cbranch_vccnz .LBB0_999
	s_lshr_b32 s84, s12, 5
	s_lshl_b32 s84, s84, 14
	s_bfe_u32 s85, s12, 0x10004
	s_lshl_b32 s85, s85, 9
	s_add_i32 s84, s84, s85
	s_add_i32 s84, s84, 96
	s_mov_b32 s85, 0
	v_cvt_pk_bf16_f32 v14, v18, v19
	v_cvt_pk_bf16_f32 v15, v20, v21
	v_lshl_add_u64 v[18:19], v[154:155], 0, s[84:85]
	global_store_dwordx2 v[18:19], v[14:15], off
.LBB0_999:
	v_fmamk_f32 v14, v17, 0x3b800000, v233
	v_mul_f32_e32 v15, 0x4b800000, v14
	v_cmp_gt_f32_e32 vcc, s25, v14
	v_lshlrev_b32_e32 v18, 16, v45
	v_and_b32_e32 v19, 0xffff0000, v45
	v_cndmask_b32_e32 v14, v14, v15, vcc
	v_rsq_f32_e32 v16, v14
	v_lshlrev_b32_e32 v14, 16, v44
	v_and_b32_e32 v15, 0xffff0000, v44
	v_mul_f32_e32 v17, 0x45800000, v16
	v_cndmask_b32_e32 v16, v16, v17, vcc
	v_pk_mul_f32 v[14:15], v[16:17], v[14:15] op_sel_hi:[0,1]
	v_pk_mul_f32 v[16:17], v[16:17], v[18:19] op_sel_hi:[0,1]
	v_add_co_u32_e32 v18, vcc, 0x1000, v32
	v_pk_mul_f32 v[16:17], v[16:17], v[8:9]
	s_nop 0
	v_addc_co_u32_e32 v19, vcc, 0, v33, vcc
	v_pk_mul_f32 v[14:15], v[14:15], v[6:7]
	s_and_b64 vcc, exec, s[10:11]
	global_store_dwordx4 v[18:19], v[14:17], off offset:3072 nt
	s_cbranch_vccnz .LBB0_1001
	s_lshr_b32 s84, s12, 5
	s_lshl_b32 s84, s84, 14
	s_bfe_u32 s85, s12, 0x10004
	s_lshl_b32 s85, s85, 9
	s_add_i32 s84, s84, s85
	s_add_i32 s84, s84, 112
	s_mov_b32 s85, 0
	v_cvt_pk_bf16_f32 v14, v14, v15
	v_cvt_pk_bf16_f32 v15, v16, v17
	v_lshl_add_u64 v[16:17], v[154:155], 0, s[84:85]
	global_store_dwordx2 v[16:17], v[14:15], off
.LBB0_1001:
	v_fmamk_f32 v10, v10, 0x3b800000, v233
	v_mul_f32_e32 v14, 0x4b800000, v10
	v_cmp_gt_f32_e32 vcc, s25, v10
	v_and_b32_e32 v15, 0xffff0000, v42
	v_and_b32_e32 v17, 0xffff0000, v43
	v_cndmask_b32_e32 v10, v10, v14, vcc
	v_rsq_f32_e32 v10, v10
	v_lshlrev_b32_e32 v14, 16, v42
	v_mul_f32_e32 v16, 0x45800000, v10
	v_cndmask_b32_e32 v10, v10, v16, vcc
	v_lshlrev_b32_e32 v16, 16, v43
	v_add_co_u32_e32 v18, vcc, 0x2000, v32
	v_pk_mul_f32 v[14:15], v[10:11], v[14:15] op_sel_hi:[0,1]
	v_pk_mul_f32 v[16:17], v[10:11], v[16:17] op_sel_hi:[0,1]
	v_addc_co_u32_e32 v19, vcc, 0, v33, vcc
	v_pk_mul_f32 v[16:17], v[16:17], v[8:9]
	v_pk_mul_f32 v[14:15], v[14:15], v[6:7]
	s_and_b64 vcc, exec, s[10:11]
	global_store_dwordx4 v[18:19], v[14:17], off nt
	s_cbranch_vccnz .LBB0_1003
	s_lshr_b32 s84, s12, 5
	s_lshl_b32 s84, s84, 14
	s_bfe_u32 s85, s12, 0x10004
	s_lshl_b32 s85, s85, 9
	s_add_i32 s84, s84, s85
	s_add_i32 s84, s84, 128
	s_mov_b32 s85, 0
	v_cvt_pk_bf16_f32 v14, v14, v15
	v_cvt_pk_bf16_f32 v15, v16, v17
	v_lshl_add_u64 v[16:17], v[154:155], 0, s[84:85]
	global_store_dwordx2 v[16:17], v[14:15], off
.LBB0_1003:
	v_fmamk_f32 v10, v11, 0x3b800000, v233
	v_mul_f32_e32 v11, 0x4b800000, v10
	v_cmp_gt_f32_e32 vcc, s25, v10
	v_lshlrev_b32_e32 v16, 16, v41
	v_and_b32_e32 v17, 0xffff0000, v41
	v_cndmask_b32_e32 v10, v10, v11, vcc
	v_rsq_f32_e32 v14, v10
	v_lshlrev_b32_e32 v10, 16, v40
	v_and_b32_e32 v11, 0xffff0000, v40
	v_mul_f32_e32 v15, 0x45800000, v14
	v_cndmask_b32_e32 v14, v14, v15, vcc
	v_pk_mul_f32 v[10:11], v[14:15], v[10:11] op_sel_hi:[0,1]
	v_pk_mul_f32 v[14:15], v[14:15], v[16:17] op_sel_hi:[0,1]
	v_pk_mul_f32 v[16:17], v[14:15], v[8:9]
	v_pk_mul_f32 v[14:15], v[10:11], v[6:7]
	v_add_co_u32_e32 v10, vcc, 0x2000, v32
	s_nop 1
	v_addc_co_u32_e32 v11, vcc, 0, v33, vcc
	s_and_b64 vcc, exec, s[10:11]
	global_store_dwordx4 v[10:11], v[14:17], off offset:1024 nt
	s_cbranch_vccnz .LBB0_1005
	s_lshr_b32 s84, s12, 5
	s_lshl_b32 s84, s84, 14
	s_bfe_u32 s85, s12, 0x10004
	s_lshl_b32 s85, s85, 9
	s_add_i32 s84, s84, s85
	s_add_i32 s84, s84, 144
	s_mov_b32 s85, 0
	v_cvt_pk_bf16_f32 v10, v14, v15
	v_cvt_pk_bf16_f32 v11, v16, v17
	v_lshl_add_u64 v[14:15], v[154:155], 0, s[84:85]
	global_store_dwordx2 v[14:15], v[10:11], off
; DEVI unsigned cvtpk(float lo, float hi) { f32x2_t v = {lo, hi}; bf16x2_t b = __builtin_convertvector(v, bf16x2_t); return __builtin_bit_cast(unsigned, b); }
; DEVI float bflo(unsigned w) { return __uint_as_float(w << 16); }
; DEVI float bfhi(unsigned w) { return __uint_as_float(w & 0xffff0000u); }
; DEVI void thin_rows(int wv, int l) {
;     ...
; #pragma unroll
;             for (int i = 0; i < 16; ++i) {
;                 const float r = rsqrtf(sq[i] * (1.f / 256.f) + EPSF);
;                 f32x4 v = {bflo(z[i].x), bfhi(z[i].x), bflo(z[i].y), bfhi(z[i].y)}; v = v * r * g;
;                 __builtin_nontemporal_store(v, (f32x4*)(d0 + (size_t)i * 256 + 4 * lane));
;                 if (samp) { u32x2 o; o.x = cvtpk(v[0], v[1]); o.y = cvtpk(v[2], v[3]); *(u32x2*)((bf16_t*)(ws + O_CKVN) + (size_t)(r0 - MP + i) * 256 + 4 * lane) = o; }
;             }
.LBB0_1005:
	v_fmamk_f32 v10, v12, 0x3b800000, v233
	v_mul_f32_e32 v11, 0x4b800000, v10
	v_cmp_gt_f32_e32 vcc, s25, v10
	v_and_b32_e32 v15, 0xffff0000, v39
	s_nop 0
	v_cndmask_b32_e32 v10, v10, v11, vcc
	v_rsq_f32_e32 v12, v10
	v_lshlrev_b32_e32 v10, 16, v38
	v_and_b32_e32 v11, 0xffff0000, v38
	v_mul_f32_e32 v14, 0x45800000, v12
	v_cndmask_b32_e32 v12, v12, v14, vcc
	v_lshlrev_b32_e32 v14, 16, v39
	v_pk_mul_f32 v[10:11], v[12:13], v[10:11] op_sel_hi:[0,1]
	v_pk_mul_f32 v[14:15], v[12:13], v[14:15] op_sel_hi:[0,1]
	v_pk_mul_f32 v[16:17], v[14:15], v[8:9]
	v_pk_mul_f32 v[14:15], v[10:11], v[6:7]
	v_add_co_u32_e32 v10, vcc, 0x2000, v32
	s_nop 1
	v_addc_co_u32_e32 v11, vcc, 0, v33, vcc
	s_and_b64 vcc, exec, s[10:11]
	global_store_dwordx4 v[10:11], v[14:17], off offset:2048 nt
	s_cbranch_vccnz .LBB0_1007
	s_lshr_b32 s84, s12, 5
	s_lshl_b32 s84, s84, 14
	s_bfe_u32 s85, s12, 0x10004
	s_lshl_b32 s85, s85, 9
	s_add_i32 s84, s84, s85
	s_add_i32 s84, s84, 160
	s_mov_b32 s85, 0
	v_cvt_pk_bf16_f32 v10, v14, v15
	v_cvt_pk_bf16_f32 v11, v16, v17
	v_lshl_add_u64 v[14:15], v[154:155], 0, s[84:85]
	global_store_dwordx2 v[14:15], v[10:11], off
.LBB0_1007:
	v_fmamk_f32 v10, v13, 0x3b800000, v233
	v_mul_f32_e32 v11, 0x4b800000, v10
	v_cmp_gt_f32_e32 vcc, s25, v10
	v_lshlrev_b32_e32 v14, 16, v37
	v_and_b32_e32 v15, 0xffff0000, v37
	v_cndmask_b32_e32 v10, v10, v11, vcc
	v_rsq_f32_e32 v12, v10
	v_lshlrev_b32_e32 v10, 16, v36
	v_and_b32_e32 v11, 0xffff0000, v36
	v_mul_f32_e32 v13, 0x45800000, v12
	v_cndmask_b32_e32 v12, v12, v13, vcc
	v_pk_mul_f32 v[10:11], v[12:13], v[10:11] op_sel_hi:[0,1]
	v_pk_mul_f32 v[12:13], v[12:13], v[14:15] op_sel_hi:[0,1]
	v_add_co_u32_e32 v14, vcc, 0x2000, v32
	v_pk_mul_f32 v[12:13], v[8:9], v[12:13]
	s_nop 0
	v_addc_co_u32_e32 v15, vcc, 0, v33, vcc
	v_pk_mul_f32 v[10:11], v[6:7], v[10:11]
	s_and_b64 vcc, exec, s[10:11]
	global_store_dwordx4 v[14:15], v[10:13], off offset:3072 nt
	s_cbranch_vccnz .LBB0_1009
	s_lshr_b32 s84, s12, 5
	s_lshl_b32 s84, s84, 14
	s_bfe_u32 s85, s12, 0x10004
	s_lshl_b32 s85, s85, 9
	s_add_i32 s84, s84, s85
	s_add_i32 s84, s84, 176
	s_mov_b32 s85, 0
	v_cvt_pk_bf16_f32 v10, v10, v11
	v_cvt_pk_bf16_f32 v11, v12, v13
	v_lshl_add_u64 v[12:13], v[154:155], 0, s[84:85]
	global_store_dwordx2 v[12:13], v[10:11], off
.LBB0_1009:
	v_fmamk_f32 v2, v2, 0x3b800000, v233
	v_mul_f32_e32 v10, 0x4b800000, v2
	v_cmp_gt_f32_e32 vcc, s25, v2
	v_and_b32_e32 v11, 0xffff0000, v34
	v_and_b32_e32 v13, 0xffff0000, v35
	v_cndmask_b32_e32 v2, v2, v10, vcc
	v_rsq_f32_e32 v2, v2
	v_lshlrev_b32_e32 v10, 16, v34
	v_mul_f32_e32 v12, 0x45800000, v2
	v_cndmask_b32_e32 v2, v2, v12, vcc
	v_lshlrev_b32_e32 v12, 16, v35
	v_add_co_u32_e32 v14, vcc, 0x3000, v32
	v_pk_mul_f32 v[10:11], v[2:3], v[10:11] op_sel_hi:[0,1]
	v_pk_mul_f32 v[12:13], v[2:3], v[12:13] op_sel_hi:[0,1]
	v_addc_co_u32_e32 v15, vcc, 0, v33, vcc
	v_pk_mul_f32 v[12:13], v[8:9], v[12:13]
	v_pk_mul_f32 v[10:11], v[6:7], v[10:11]
	s_and_b64 vcc, exec, s[10:11]
	global_store_dwordx4 v[14:15], v[10:13], off nt
	s_cbranch_vccnz .LBB0_1011
	s_lshr_b32 s84, s12, 5
	s_lshl_b32 s84, s84, 14
	s_bfe_u32 s85, s12, 0x10004
	s_lshl_b32 s85, s85, 9
	s_add_i32 s84, s84, s85
	s_add_i32 s84, s84, 192
	s_mov_b32 s85, 0
	v_cvt_pk_bf16_f32 v10, v10, v11
	v_cvt_pk_bf16_f32 v11, v12, v13
	v_lshl_add_u64 v[12:13], v[154:155], 0, s[84:85]
	global_store_dwordx2 v[12:13], v[10:11], off
.LBB0_1011:
	v_fmamk_f32 v2, v3, 0x3b800000, v233
	v_mul_f32_e32 v3, 0x4b800000, v2
	v_cmp_gt_f32_e32 vcc, s25, v2
	v_lshlrev_b32_e32 v12, 16, v31
	v_and_b32_e32 v13, 0xffff0000, v31
	v_cndmask_b32_e32 v2, v2, v3, vcc
	v_rsq_f32_e32 v10, v2
	v_lshlrev_b32_e32 v2, 16, v30
	v_and_b32_e32 v3, 0xffff0000, v30
	v_mul_f32_e32 v11, 0x45800000, v10
	v_cndmask_b32_e32 v10, v10, v11, vcc
	v_pk_mul_f32 v[2:3], v[10:11], v[2:3] op_sel_hi:[0,1]
	v_pk_mul_f32 v[10:11], v[10:11], v[12:13] op_sel_hi:[0,1]
	v_pk_mul_f32 v[12:13], v[8:9], v[10:11]
	v_pk_mul_f32 v[10:11], v[6:7], v[2:3]
	v_add_co_u32_e32 v2, vcc, 0x3000, v32
	s_nop 1
	v_addc_co_u32_e32 v3, vcc, 0, v33, vcc
	s_and_b64 vcc, exec, s[10:11]
	global_store_dwordx4 v[2:3], v[10:13], off offset:1024 nt
	s_cbranch_vccnz .LBB0_1013
	s_lshr_b32 s84, s12, 5
	s_lshl_b32 s84, s84, 14
	s_bfe_u32 s85, s12, 0x10004
	s_lshl_b32 s85, s85, 9
	s_add_i32 s84, s84, s85
	s_add_i32 s84, s84, 208
	s_mov_b32 s85, 0
	v_cvt_pk_bf16_f32 v2, v10, v11
	v_cvt_pk_bf16_f32 v3, v12, v13
	v_lshl_add_u64 v[10:11], v[154:155], 0, s[84:85]
	global_store_dwordx2 v[10:11], v[2:3], off
.LBB0_1013:
	v_fmamk_f32 v2, v4, 0x3b800000, v233
	v_mul_f32_e32 v3, 0x4b800000, v2
	v_cmp_gt_f32_e32 vcc, s25, v2
	v_and_b32_e32 v11, 0xffff0000, v29
	s_nop 0
	v_cndmask_b32_e32 v2, v2, v3, vcc
	v_rsq_f32_e32 v4, v2
	v_lshlrev_b32_e32 v2, 16, v28
	v_and_b32_e32 v3, 0xffff0000, v28
	v_mul_f32_e32 v10, 0x45800000, v4
	v_cndmask_b32_e32 v4, v4, v10, vcc
	v_lshlrev_b32_e32 v10, 16, v29
	v_pk_mul_f32 v[2:3], v[4:5], v[2:3] op_sel_hi:[0,1]
	v_pk_mul_f32 v[10:11], v[4:5], v[10:11] op_sel_hi:[0,1]
	v_pk_mul_f32 v[12:13], v[8:9], v[10:11]
	v_pk_mul_f32 v[10:11], v[6:7], v[2:3]
	v_add_co_u32_e32 v2, vcc, 0x3000, v32
	s_nop 1
	v_addc_co_u32_e32 v3, vcc, 0, v33, vcc
	s_and_b64 vcc, exec, s[10:11]
	global_store_dwordx4 v[2:3], v[10:13], off offset:2048 nt
	s_cbranch_vccnz .LBB0_1015
	s_lshr_b32 s84, s12, 5
	s_lshl_b32 s84, s84, 14
	s_bfe_u32 s85, s12, 0x10004
	s_lshl_b32 s85, s85, 9
	s_add_i32 s84, s84, s85
	s_add_i32 s84, s84, 224
	s_mov_b32 s85, 0
	v_cvt_pk_bf16_f32 v2, v10, v11
	v_cvt_pk_bf16_f32 v3, v12, v13
	v_lshl_add_u64 v[10:11], v[154:155], 0, s[84:85]
	global_store_dwordx2 v[10:11], v[2:3], off
.LBB0_1015:
	v_fmamk_f32 v2, v5, 0x3b800000, v233
	v_mul_f32_e32 v3, 0x4b800000, v2
	v_cmp_gt_f32_e32 vcc, s25, v2
	v_lshlrev_b32_e32 v10, 16, v27
	v_and_b32_e32 v11, 0xffff0000, v27
	v_cndmask_b32_e32 v2, v2, v3, vcc
	v_rsq_f32_e32 v4, v2
	v_lshlrev_b32_e32 v2, 16, v26
	v_and_b32_e32 v3, 0xffff0000, v26
	v_mul_f32_e32 v5, 0x45800000, v4
	v_cndmask_b32_e32 v4, v4, v5, vcc
	v_pk_mul_f32 v[2:3], v[4:5], v[2:3] op_sel_hi:[0,1]
	v_pk_mul_f32 v[2:3], v[6:7], v[2:3]
	v_add_co_u32_e32 v6, vcc, 0x3000, v32
	v_pk_mul_f32 v[4:5], v[4:5], v[10:11] op_sel_hi:[0,1]
	s_nop 0
	v_addc_co_u32_e32 v7, vcc, 0, v33, vcc
	v_pk_mul_f32 v[4:5], v[8:9], v[4:5]
	s_and_b64 vcc, exec, s[10:11]
	global_store_dwordx4 v[6:7], v[2:5], off offset:3072 nt
	s_cbranch_vccnz .LBB0_1017
	s_lshr_b32 s10, s12, 5
	s_lshl_b32 s10, s10, 14
	s_bfe_u32 s11, s12, 0x10004
	s_lshl_b32 s11, s11, 9
	s_add_i32 s10, s10, s11
	s_add_i32 s10, s10, 240
	s_mov_b32 s11, 0
	v_cvt_pk_bf16_f32 v2, v2, v3
	v_cvt_pk_bf16_f32 v3, v4, v5
	v_lshl_add_u64 v[4:5], v[154:155], 0, s[10:11]
	global_store_dwordx2 v[4:5], v[2:3], off

; DEVI const float* IN(int i) { return *(const float* const __attribute__((address_space(4)))*)(kargs() + 8 * i); }
; DEVI float* OUTP() { return *(float* const __attribute__((address_space(4)))*)(kargs() + 8 * 21); }
; DEVI void sample_attn_fused(int wv, LAS unsigned char* lds, int l, int bh) {
;     ...
;     const bf16_t* cache_c = (const bf16_t*)(ws + O_CKVB) + ((size_t)l * MC + (size_t)b * 4096) * 256;
;     const float* cache_r = IN(3) + ((size_t)l * MC + (size_t)b * 4096) * 32;
;     const bf16_t* new_c = (const bf16_t*)(ws + O_CKVN) + (size_t)(b * 16 + (r32 & 15)) * 256;
;     const float* new_r = OUTP() + OUT_KRS + ((size_t)l * MS + b * 16 + (r32 & 15)) * 32;
;     ...
;     bf16x8 cf[16]; f32x4 kr0, kr1, kr2, kr3;
;     {
;         const bf16_t* cp = FS_CP(w); const float* rp = FS_RP(w);
; #pragma unroll
;         for (int ks = 0; ks < 16; ++ks) cf[ks] = *(const bf16x8*)(cp + FS_KO(ks));
;         kr0 = *(const f32x4*)rp; kr1 = *(const f32x4*)(rp + 4); kr2 = *(const f32x4*)(rp + 16); kr3 = *(const f32x4*)(rp + 20);
;     }
;     float m_run = -INFINITY, l_run = 0.f;
;     f32x16 o0, o1;
; #pragma unroll
;     for (int r = 0; r < 16; ++r) { o0[r] = 0.f; o1[r] = 0.f; }
.LBB0_1341:
	s_andn2_b64 vcc, exec, s[58:59]
	s_cbranch_vccnz .LBB0_1379
	s_cmpk_eq_i32 s5, 0x80
	s_load_dwordx2 s[42:43], s[56:57], 0x18
	s_cselect_b64 vcc, -1, 0
	s_ashr_i32 s3, s2, 31
	s_lshl_b64 s[2:3], s[2:3], 12
	s_add_u32 s56, s2, s6
	s_addc_u32 s57, s3, s7
	s_lshl_b64 s[2:3], s[56:57], 7
	s_waitcnt lgkmcnt(0)
	s_add_u32 s2, s42, s2
	s_addc_u32 s3, s43, s3
	s_load_dwordx2 s[42:43], s[54:55], 0xa8
	s_add_u32 s12, s8, s36
	s_addc_u32 s27, s9, s38
	v_mov_b32_e32 v7, s27
	v_or_b32_e32 v6, s12, v47
	v_lshlrev_b64 v[6:7], 7, v[6:7]
	s_waitcnt lgkmcnt(0)
	v_lshl_add_u64 v[6:7], s[42:43], 0, v[6:7]
	s_mov_b64 s[42:43], 0xcb78000
	v_lshl_add_u64 v[6:7], v[6:7], 0, s[42:43]
	s_lshl_b64 s[42:43], s[56:57], 9
	v_lshl_or_b32 v2, s5, 5, v173
	s_add_u32 s12, s50, s42
	v_or_b32_e32 v8, s36, v47
	v_ashrrev_i32_e32 v3, 31, v2
	s_addc_u32 s27, s51, s43
	v_lshrrev_b32_e32 v9, 5, v8
	v_lshlrev_b64 v[4:5], 7, v[2:3]
	s_add_u32 s42, s12, 0x3bb0800
	v_lshlrev_b32_e32 v9, 14, v9
	v_bfe_u32 v188, v8, 4, 1
	v_lshl_or_b32 v9, v188, 9, v9
	v_and_b32_e32 v188, 15, v8
	v_lshl_or_b32 v8, v188, 4, v9
	v_mov_b32_e32 v9, 0
	v_lshl_add_u64 v[4:5], s[2:3], 0, v[4:5]
	s_addc_u32 s43, s27, 0
	v_mov_b32_e32 v2, s5
	v_lshlrev_b32_e32 v2, 14, v2
	v_mov_b32_e32 v3, 0
	v_lshl_add_u64 v[8:9], s[50:51], 0, v[8:9]
	s_mov_b64 s[54:55], 0x3ce90800
	v_cndmask_b32_e32 v5, v5, v7, vcc
	v_cndmask_b32_e32 v4, v4, v6, vcc
	v_lshl_add_u64 v[2:3], s[42:43], 0, v[2:3]
	v_lshl_add_u64 v[8:9], v[8:9], 0, s[54:55]
	v_and_b32_e32 v0, 32, v172
	v_mov_b32_e32 v47, v1
	v_cndmask_b32_e32 v3, v3, v9, vcc
	v_cndmask_b32_e32 v2, v2, v8, vcc
	v_lshlrev_b32_e32 v0, 1, v0
	v_lshl_add_u64 v[4:5], v[4:5], 0, v[46:47]
	v_lshlrev_b32_e32 v188, 4, v175
	v_lshlrev_b32_e32 v190, 8, v56
	v_add_u32_e32 v188, 0x1000, v188
	v_add_u32_e32 v190, 0x1000, v190
	v_mov_b32_e32 v189, 0
	v_mov_b32_e32 v191, 0
	v_cndmask_b32_e32 v192, v188, v190, vcc
	v_mov_b32_e32 v193, 0
	v_lshl_add_u64 v[2:3], v[2:3], 0, v[192:193]
	v_add_co_u32_e32 v194, vcc, 0x2000, v2
	s_nop 1
	v_addc_co_u32_e32 v195, vcc, 0, v3, vcc
	global_load_dwordx4 v[86:89], v[4:5], off offset:80
	global_load_dwordx4 v[94:97], v[4:5], off offset:64
	global_load_dwordx4 v[82:85], v[4:5], off offset:16
	global_load_dwordx4 v[90:93], v[4:5], off
	global_load_dwordx4 v[158:161], v[2:3], off offset:-4096
	global_load_dwordx4 v[154:157], v[2:3], off offset:-3072
	global_load_dwordx4 v[150:153], v[2:3], off offset:-2048
	global_load_dwordx4 v[146:149], v[2:3], off offset:-1024
	global_load_dwordx4 v[142:145], v[2:3], off
	global_load_dwordx4 v[138:141], v[2:3], off offset:1024
	global_load_dwordx4 v[134:137], v[2:3], off offset:2048
	global_load_dwordx4 v[130:133], v[2:3], off offset:3072
	global_load_dwordx4 v[126:129], v[194:195], off offset:-4096
	global_load_dwordx4 v[122:125], v[194:195], off offset:-3072
	global_load_dwordx4 v[118:121], v[194:195], off offset:-2048
	global_load_dwordx4 v[114:117], v[194:195], off offset:-1024
	global_load_dwordx4 v[110:113], v[194:195], off
	global_load_dwordx4 v[106:109], v[194:195], off offset:1024
	global_load_dwordx4 v[102:105], v[194:195], off offset:2048
	global_load_dwordx4 v[98:101], v[194:195], off offset:3072
	v_mul_u32_u24_e32 v2, 0x210, v173
	v_lshlrev_b32_e32 v3, 6, v56
	v_add3_u32 v178, 0, v2, v3
	v_and_b32_e32 v2, 64, v238
	v_lshl_add_u64 v[162:163], v[8:9], 0, v[190:191]
	v_lshl_add_u64 v[164:165], s[42:43], 0, v[188:189]
	v_xor_b32_e32 v0, 32, v238
	v_add_u32_e32 v177, 64, v2
	v_cmp_lt_i32_e32 vcc, v0, v177
	v_mov_b32_e32 v180, 0
	v_lshl_add_u64 v[166:167], v[6:7], 0, v[46:47]
	v_cndmask_b32_e32 v2, v238, v0, vcc
	v_lshl_add_u64 v[168:169], s[2:3], 0, v[46:47]
	v_lshlrev_b32_e32 v179, 2, v2
	v_mov_b32_e32 v181, 0xff800000
	s_mov_b32 s27, s5
	v_mov_b32_e32 v2, 0
	v_mov_b32_e32 v3, v180
	v_mov_b32_e32 v4, v180
	v_mov_b32_e32 v5, v180
	v_mov_b32_e32 v6, v180
	v_mov_b32_e32 v7, v180
	v_mov_b32_e32 v8, v180
	v_mov_b32_e32 v9, v180
	v_mov_b32_e32 v10, v180
	v_mov_b32_e32 v11, v180
	v_mov_b32_e32 v12, v180
	v_mov_b32_e32 v13, v180
	v_mov_b32_e32 v14, v180
	v_mov_b32_e32 v15, v180
	v_mov_b32_e32 v16, v180
	v_mov_b32_e32 v17, v180
	v_mov_b32_e32 v18, 0
	v_mov_b32_e32 v19, v180
	v_mov_b32_e32 v20, v180
	v_mov_b32_e32 v21, v180
	v_mov_b32_e32 v22, v180
	v_mov_b32_e32 v23, v180
	v_mov_b32_e32 v24, v180
	v_mov_b32_e32 v25, v180
	v_mov_b32_e32 v26, v180
	v_mov_b32_e32 v27, v180
	v_mov_b32_e32 v28, v180
	v_mov_b32_e32 v29, v180
	v_mov_b32_e32 v30, v180
	v_mov_b32_e32 v31, v180
	v_mov_b32_e32 v32, v180
	v_mov_b32_e32 v33, v180
; #define LAS __attribute__((address_space(3)))
; DEVI float ss4(const f32x4 a) { return (a[0] * a[0] + a[1] * a[1]) + (a[2] * a[2] + a[3] * a[3]); }
; #define MFMA32(a, b, c) __builtin_amdgcn_mfma_f32_32x32x16_bf16((a), (b), (c), 0, 0, 0)
; DEVI void sample_attn_fused(int wv, LAS unsigned char* lds, int l, int bh) {
;     ...
;     for (int kb = w; kb < FS_NBLK; kb += 8) {
;         const int nkb = kb + 8; const bool more = nkb < FS_NBLK;
;         const bf16_t* ncp = FS_CP(more ? nkb : kb); const float* nrp = FS_RP(more ? nkb : kb);
;         f32x16 x0, x1;
; #pragma unroll
;         for (int r = 0; r < 16; ++r) { x0[r] = 0.f; x1[r] = 0.f; }
; #pragma unroll
;         for (int ks = 0; ks < 16; ++ks) {
;             const bf16x8 a0 = *(const LAS bf16x8*)(wkl + 2 * FS_KO(ks)), a1 = *(const LAS bf16x8*)(wkl + 32 * FS_PITCH + 2 * FS_KO(ks));
;             x0 = MFMA32(a0, cf[ks], x0); x1 = MFMA32(a1, cf[ks], x1);
;             if ((ks & 3) == 3) __builtin_amdgcn_sched_barrier(0);
;         }
;         float ss = (ss4(kr0) + ss4(kr1)) + (ss4(kr2) + ss4(kr3));
; #pragma unroll
;         for (int r = 0; r < 16; ++r) ss += x0[r] * x0[r] + x1[r] * x1[r];
;         ss += __shfl_xor(ss, 32);
.LBB0_1343:
	ds_read_b128 v[34:37], v178
	ds_read_b128 v[38:41], v178 offset:16
	s_add_i32 s12, s27, 8
	s_cmpk_gt_i32 s27, 0x78
	s_cselect_b64 s[54:55], -1, 0
	s_waitcnt vmcnt(0) lgkmcnt(1)
	v_mfma_f32_32x32x16_bf16 v[66:81], v[34:37], v[158:161], 0
	ds_read_b128 v[34:37], v178 offset:16896
	ds_read_b128 v[42:45], v178 offset:16912
	s_cmpk_lt_i32 s27, 0x79
	s_cselect_b64 s[56:57], -1, 0
	s_and_b64 s[2:3], s[56:57], exec
	s_cselect_b32 s36, s12, s27
	s_cmpk_lt_i32 s36, 0x80
	v_lshl_or_b32 v170, s36, 5, v173
	s_waitcnt lgkmcnt(1)
	v_mfma_f32_32x32x16_bf16 v[50:65], v[34:37], v[158:161], 0
	s_cselect_b64 s[2:3], -1, 0
	v_ashrrev_i32_e32 v171, 31, v170
	s_lshl_b32 vcc_lo, s36, 14
	s_mov_b32 vcc_hi, 0
	v_lshl_add_u64 v[190:191], vcc, 0, v[164:165]
	v_cndmask_b32_e64 v191, v163, v191, s[2:3]
	v_cndmask_b32_e64 v190, v162, v190, s[2:3]
	v_add_co_u32_e32 v192, vcc, 0x2000, v190
	s_nop 1
	v_addc_co_u32_e32 v193, vcc, 0, v191, vcc
	v_mfma_f32_32x32x16_bf16 v[66:81], v[38:41], v[154:157], v[66:81]
	ds_read_b128 v[34:37], v178 offset:32
	ds_read_b128 v[38:41], v178 offset:48
	s_waitcnt lgkmcnt(2)
	v_mfma_f32_32x32x16_bf16 v[50:65], v[42:45], v[154:157], v[50:65]
	s_waitcnt lgkmcnt(1)
	v_mfma_f32_32x32x16_bf16 v[66:81], v[34:37], v[150:153], v[66:81]
	ds_read_b128 v[34:37], v178 offset:16928
	ds_read_b128 v[42:45], v178 offset:16944
	s_waitcnt lgkmcnt(1)
	v_mfma_f32_32x32x16_bf16 v[50:65], v[34:37], v[150:153], v[50:65]
	v_mfma_f32_32x32x16_bf16 v[66:81], v[38:41], v[146:149], v[66:81]
	s_waitcnt lgkmcnt(0)
	v_mfma_f32_32x32x16_bf16 v[50:65], v[42:45], v[146:149], v[50:65]
	ds_read_b128 v[34:37], v178 offset:128
	ds_read_b128 v[38:41], v178 offset:144
	s_waitcnt lgkmcnt(1)
	v_mfma_f32_32x32x16_bf16 v[66:81], v[34:37], v[142:145], v[66:81]
	ds_read_b128 v[34:37], v178 offset:17024
	ds_read_b128 v[42:45], v178 offset:17040
	s_waitcnt lgkmcnt(1)
	v_mfma_f32_32x32x16_bf16 v[50:65], v[34:37], v[142:145], v[50:65]
	v_mfma_f32_32x32x16_bf16 v[66:81], v[38:41], v[138:141], v[66:81]
	ds_read_b128 v[34:37], v178 offset:160
	ds_read_b128 v[38:41], v178 offset:176
	s_waitcnt lgkmcnt(2)
	v_mfma_f32_32x32x16_bf16 v[50:65], v[42:45], v[138:141], v[50:65]
	s_waitcnt lgkmcnt(1)
	v_mfma_f32_32x32x16_bf16 v[66:81], v[34:37], v[134:137], v[66:81]
	ds_read_b128 v[34:37], v178 offset:17056
	ds_read_b128 v[42:45], v178 offset:17072
	s_waitcnt lgkmcnt(1)
	v_mfma_f32_32x32x16_bf16 v[50:65], v[34:37], v[134:137], v[50:65]
	v_mfma_f32_32x32x16_bf16 v[66:81], v[38:41], v[130:133], v[66:81]
	s_waitcnt lgkmcnt(0)
	v_mfma_f32_32x32x16_bf16 v[50:65], v[42:45], v[130:133], v[50:65]
	ds_read_b128 v[34:37], v178 offset:256
	ds_read_b128 v[38:41], v178 offset:272
	s_waitcnt lgkmcnt(1)
	v_mfma_f32_32x32x16_bf16 v[66:81], v[34:37], v[126:129], v[66:81]
	ds_read_b128 v[34:37], v178 offset:17152
	ds_read_b128 v[42:45], v178 offset:17168
	s_waitcnt lgkmcnt(1)
	v_mfma_f32_32x32x16_bf16 v[50:65], v[34:37], v[126:129], v[50:65]
	v_mfma_f32_32x32x16_bf16 v[66:81], v[38:41], v[122:125], v[66:81]
	ds_read_b128 v[34:37], v178 offset:288
	ds_read_b128 v[38:41], v178 offset:304
	s_waitcnt lgkmcnt(2)
	v_mfma_f32_32x32x16_bf16 v[50:65], v[42:45], v[122:125], v[50:65]
	s_waitcnt lgkmcnt(1)
	v_mfma_f32_32x32x16_bf16 v[66:81], v[34:37], v[118:121], v[66:81]
	ds_read_b128 v[34:37], v178 offset:17184
	ds_read_b128 v[42:45], v178 offset:17200
	s_waitcnt lgkmcnt(1)
	v_mfma_f32_32x32x16_bf16 v[50:65], v[34:37], v[118:121], v[50:65]
	v_mfma_f32_32x32x16_bf16 v[66:81], v[38:41], v[114:117], v[66:81]
	s_waitcnt lgkmcnt(0)
	v_mfma_f32_32x32x16_bf16 v[50:65], v[42:45], v[114:117], v[50:65]
	ds_read_b128 v[34:37], v178 offset:384
	ds_read_b128 v[38:41], v178 offset:400
	s_waitcnt lgkmcnt(1)
	v_mfma_f32_32x32x16_bf16 v[66:81], v[34:37], v[110:113], v[66:81]
	ds_read_b128 v[34:37], v178 offset:17280
	ds_read_b128 v[42:45], v178 offset:17296
	s_waitcnt lgkmcnt(1)
	v_mfma_f32_32x32x16_bf16 v[50:65], v[34:37], v[110:113], v[50:65]
	v_mfma_f32_32x32x16_bf16 v[66:81], v[38:41], v[106:109], v[66:81]
	ds_read_b128 v[34:37], v178 offset:416
	ds_read_b128 v[38:41], v178 offset:432
	s_waitcnt lgkmcnt(2)
	v_mfma_f32_32x32x16_bf16 v[50:65], v[42:45], v[106:109], v[50:65]
	s_waitcnt lgkmcnt(1)
	v_mfma_f32_32x32x16_bf16 v[66:81], v[34:37], v[102:105], v[66:81]
	ds_read_b128 v[34:37], v178 offset:17312
	ds_read_b128 v[42:45], v178 offset:17328
	s_waitcnt lgkmcnt(1)
	v_mfma_f32_32x32x16_bf16 v[50:65], v[34:37], v[102:105], v[50:65]
	v_mfma_f32_32x32x16_bf16 v[66:81], v[38:41], v[98:101], v[66:81]
	s_waitcnt lgkmcnt(0)
	v_mfma_f32_32x32x16_bf16 v[50:65], v[42:45], v[98:101], v[50:65]
	v_mul_f32_e32 v34, v91, v91
	v_mul_f32_e32 v35, v93, v93
	v_fmac_f32_e32 v34, v90, v90
	v_fmac_f32_e32 v35, v92, v92
	v_add_f32_e32 v34, v34, v35
	v_mul_f32_e32 v35, v83, v83
	v_mul_f32_e32 v36, v85, v85
	v_fmac_f32_e32 v35, v82, v82
	v_fmac_f32_e32 v36, v84, v84
	v_add_f32_e32 v35, v35, v36
	v_add_f32_e32 v34, v34, v35
	v_mul_f32_e32 v35, v95, v95
	v_mul_f32_e32 v36, v97, v97
	v_fmac_f32_e32 v35, v94, v94
	v_fmac_f32_e32 v36, v96, v96
	v_add_f32_e32 v35, v35, v36
	v_mul_f32_e32 v36, v87, v87
	v_mul_f32_e32 v37, v89, v89
	v_fmac_f32_e32 v36, v86, v86
	v_fmac_f32_e32 v37, v88, v88
	v_add_f32_e32 v36, v36, v37
	v_add_f32_e32 v35, v35, v36
	v_add_f32_e32 v34, v34, v35
	v_mul_f32_e32 v35, v50, v50
	v_fmac_f32_e32 v35, v66, v66
	v_add_f32_e32 v34, v34, v35
	v_mul_f32_e32 v35, v51, v51
	v_fmac_f32_e32 v35, v67, v67
	v_add_f32_e32 v34, v35, v34
	v_mul_f32_e32 v35, v52, v52
	v_fmac_f32_e32 v35, v68, v68
	v_add_f32_e32 v34, v35, v34
	v_mul_f32_e32 v35, v53, v53
	v_fmac_f32_e32 v35, v69, v69
	v_add_f32_e32 v34, v35, v34
	v_mul_f32_e32 v35, v54, v54
	v_fmac_f32_e32 v35, v70, v70
	v_add_f32_e32 v34, v35, v34
	v_mul_f32_e32 v35, v55, v55
	v_fmac_f32_e32 v35, v71, v71
	v_add_f32_e32 v44, v35, v34
	v_pk_mul_f32 v[34:35], v[56:57], v[56:57]
	v_pk_mul_f32 v[36:37], v[58:59], v[58:59]
	v_pk_fma_f32 v[34:35], v[72:73], v[72:73], v[34:35]
	v_pk_fma_f32 v[36:37], v[74:75], v[74:75], v[36:37]
	v_add_f32_e32 v34, v34, v44
	v_add_f32_e32 v34, v35, v34
	v_pk_mul_f32 v[38:39], v[60:61], v[60:61]
	v_add_f32_e32 v34, v36, v34
	v_pk_fma_f32 v[38:39], v[76:77], v[76:77], v[38:39]
	v_add_f32_e32 v34, v37, v34
	v_pk_mul_f32 v[40:41], v[62:63], v[62:63]
	v_add_f32_e32 v34, v38, v34
	v_pk_fma_f32 v[40:41], v[78:79], v[78:79], v[40:41]
	v_add_f32_e32 v34, v39, v34
	v_pk_mul_f32 v[42:43], v[64:65], v[64:65]
	v_add_f32_e32 v34, v40, v34
	v_pk_fma_f32 v[42:43], v[80:81], v[80:81], v[42:43]
	v_add_f32_e32 v34, v41, v34
	v_add_f32_e32 v34, v42, v34
	v_add_f32_e32 v34, v43, v34
	ds_bpermute_b32 v35, v179, v34
	s_waitcnt lgkmcnt(0)
; #define LAS __attribute__((address_space(3)))
; DEVI u32x4 pack8(const f32x4 a, const f32x4 b) { u32x4 w; w.x = cvtpk(a[0], a[1]); w.y = cvtpk(a[2], a[3]); w.z = cvtpk(b[0], b[1]); w.w = cvtpk(b[2], b[3]); return w; }
; #define MFMA32(a, b, c) __builtin_amdgcn_mfma_f32_32x32x16_bf16((a), (b), (c), 0, 0, 0)
; DEVI void sample_attn_fused(int wv, LAS unsigned char* lds, int l, int bh) {
;     ...
;         ss += __shfl_xor(ss, 32);
;         const float sk = rsqrtf(ss * (1.f / 96.f) + EPSF);
;         f32x16 p;
; #pragma unroll
;         for (int r = 0; r < 16; ++r) p[r] = 0.f;
;         p = MFMA32(pk_regs(x0, 0, sk), qf[0], p); p = MFMA32(pk_regs(x0, 1, sk), qf[64], p);
;         p = MFMA32(pk_regs(x1, 0, sk), qf[128], p); p = MFMA32(pk_regs(x1, 1, sk), qf[192], p);
;         { const u32x4 k0 = pack8(kr0 * sk, kr1 * sk), k1 = pack8(kr2 * sk, kr3 * sk);
;           p = MFMA32(__builtin_bit_cast(bf16x8, k0), qf[256], p); p = MFMA32(__builtin_bit_cast(bf16x8, k1), qf[320], p); }
;         if (more) { kr0 = *(const f32x4*)nrp; kr1 = *(const f32x4*)(nrp + 4); kr2 = *(const f32x4*)(nrp + 16); kr3 = *(const f32x4*)(nrp + 20); }
;         if (kb == 128) {
; #pragma unroll
;             for (int r = 8; r < 16; ++r) p[r] = -INFINITY;
;         }
;         float mx = p[0];
; #pragma unroll
;         for (int r = 1; r < 16; ++r) mx = fmaxf(mx, p[r]);
;         mx = fmaxf(mx, __shfl_xor(mx, 32));
;         const float mn = fmaxf(m_run, mx), alpha = __builtin_amdgcn_exp2f(m_run - mn);
;         m_run = mn;
;         float rs = 0.f;
; #pragma unroll
;         for (int r = 0; r < 16; ++r) { p[r] = __builtin_amdgcn_exp2f(p[r] - mn); rs += p[r]; }
;         l_run = l_run * alpha + rs;
; #pragma unroll
;         for (int r = 0; r < 16; ++r) { o0[r] *= alpha; o1[r] *= alpha; }
;         const bf16x8 pb0 = pk_regs(p, 0, 1.f), pb1 = pk_regs(p, 1, 1.f);
;         {
;             f32x16 v;
; #pragma unroll
;             for (int r = 0; r < 16; ++r) v[r] = 0.f;
; #pragma unroll
;             for (int ks = 0; ks < 16; ++ks) { v = MFMA32(cf[ks], *(const LAS bf16x8*)(wvl + 2 * FS_KO(ks)), v); if ((ks & 3) == 3) __builtin_amdgcn_sched_barrier(0); }
;             o0 = MFMA32(pk_regs(v, 0, 1.f), pb0, o0); o0 = MFMA32(pk_regs(v, 1, 1.f), pb1, o0);
	v_add_f32_e32 v34, v34, v35
	v_fmamk_f32 v34, v34, 0x3c2aaaab, v233
	v_mul_f32_e32 v35, 0x4b800000, v34
	v_cmp_gt_f32_e32 vcc, s25, v34
	s_nop 1
	v_cndmask_b32_e32 v34, v34, v35, vcc
	v_rsq_f32_e32 v34, v34
	s_nop 0
	v_mul_f32_e32 v35, 0x45800000, v34
	v_cndmask_b32_e32 v182, v34, v35, vcc
	v_pk_mul_f32 v[34:35], v[66:67], v[182:183] op_sel_hi:[1,0]
	v_pk_mul_f32 v[36:37], v[68:69], v[182:183] op_sel_hi:[1,0]
	v_cvt_pk_bf16_f32 v34, v34, v35
	v_cvt_pk_bf16_f32 v35, v36, v37
	v_pk_mul_f32 v[36:37], v[70:71], v[182:183] op_sel_hi:[1,0]
	v_pk_mul_f32 v[38:39], v[72:73], v[182:183] op_sel_hi:[1,0]
	v_cvt_pk_bf16_f32 v36, v36, v37
	v_cvt_pk_bf16_f32 v37, v38, v39
	ds_read_b128 v[38:41], v176
	ds_read_b128 v[66:69], v176 offset:1024
	s_waitcnt lgkmcnt(1)
	v_mfma_f32_32x32x16_bf16 v[34:49], v[34:37], v[38:41], 0
	v_mul_f32_e64 v70, v74, v182
	v_mul_f32_e64 v71, v75, v182
	v_mul_f32_e64 v72, v76, v182
	v_mul_f32_e64 v73, v77, v182
	v_cvt_pk_bf16_f32 v70, v70, v71
	v_cvt_pk_bf16_f32 v71, v72, v73
	v_pk_mul_f32 v[72:73], v[78:79], v[182:183] op_sel_hi:[1,0]
	v_pk_mul_f32 v[74:75], v[80:81], v[182:183] op_sel_hi:[1,0]
	v_cvt_pk_bf16_f32 v72, v72, v73
	v_cvt_pk_bf16_f32 v73, v74, v75
	v_pk_mul_f32 v[50:51], v[50:51], v[182:183] op_sel_hi:[1,0]
	v_pk_mul_f32 v[52:53], v[52:53], v[182:183] op_sel_hi:[1,0]
	s_waitcnt lgkmcnt(0)
	v_mfma_f32_32x32x16_bf16 v[34:49], v[70:73], v[66:69], v[34:49]
	v_cvt_pk_bf16_f32 v50, v50, v51
	v_cvt_pk_bf16_f32 v51, v52, v53
	v_mul_f32_e64 v52, v54, v182
	v_mul_f32_e64 v53, v55, v182
	v_mul_f32_e64 v54, v56, v182
	v_mul_f32_e64 v55, v57, v182
	v_cvt_pk_bf16_f32 v52, v52, v53
	v_cvt_pk_bf16_f32 v53, v54, v55
	ds_read_b128 v[54:57], v176 offset:2048
	ds_read_b128 v[66:69], v176 offset:3072
	s_waitcnt lgkmcnt(1)
	v_mfma_f32_32x32x16_bf16 v[34:49], v[50:53], v[54:57], v[34:49]
	v_mul_f32_e64 v50, v58, v182
	v_mul_f32_e64 v51, v59, v182
	v_mul_f32_e64 v52, v60, v182
	v_mul_f32_e64 v53, v61, v182
	v_cvt_pk_bf16_f32 v50, v50, v51
	v_cvt_pk_bf16_f32 v51, v52, v53
	v_pk_mul_f32 v[52:53], v[62:63], v[182:183] op_sel_hi:[1,0]
	v_pk_mul_f32 v[54:55], v[64:65], v[182:183] op_sel_hi:[1,0]
	v_cvt_pk_bf16_f32 v52, v52, v53
	v_cvt_pk_bf16_f32 v53, v54, v55
	v_pk_mul_f32 v[54:55], v[84:85], v[182:183] op_sel_hi:[1,0]
	v_pk_mul_f32 v[56:57], v[82:83], v[182:183] op_sel_hi:[1,0]
	s_waitcnt lgkmcnt(0)
	v_mfma_f32_32x32x16_bf16 v[34:49], v[50:53], v[66:69], v[34:49]
	v_mul_f32_e64 v52, v92, v182
	v_mul_f32_e64 v53, v93, v182
	v_mul_f32_e64 v50, v90, v182
	v_mul_f32_e64 v51, v91, v182
	ds_read_b128 v[62:65], v176 offset:5120
	v_cvt_pk_bf16_f32 v50, v50, v51
	v_cvt_pk_bf16_f32 v51, v52, v53
	v_cvt_pk_bf16_f32 v52, v56, v57
	v_cvt_pk_bf16_f32 v53, v54, v55
	ds_read_b128 v[54:57], v176 offset:4096
	v_pk_mul_f32 v[60:61], v[96:97], v[182:183] op_sel_hi:[1,0]
	s_waitcnt lgkmcnt(0)
	v_mfma_f32_32x32x16_bf16 v[34:49], v[50:53], v[54:57], v[34:49]
	v_mul_f32_e64 v58, v94, v182
	v_mul_f32_e64 v59, v95, v182
	v_mul_f32_e64 v66, v88, v182
	v_mul_f32_e64 v67, v89, v182
	v_mul_f32_e64 v68, v86, v182
	v_mul_f32_e64 v69, v87, v182
	v_cvt_pk_bf16_f32 v58, v58, v59
	v_cvt_pk_bf16_f32 v59, v60, v61
	v_cvt_pk_bf16_f32 v60, v68, v69
	v_cvt_pk_bf16_f32 v61, v66, v67
	s_and_b64 vcc, exec, s[54:55]
	s_nop 0
	v_mfma_f32_32x32x16_bf16 v[34:49], v[58:61], v[62:65], v[34:49]
	s_cbranch_vccnz .LBB0_1345
	v_lshlrev_b64 v[50:51], 7, v[170:171]
	v_lshl_add_u64 v[50:51], v[168:169], 0, v[50:51]
	v_cndmask_b32_e64 v51, v167, v51, s[2:3]
	v_cndmask_b32_e64 v50, v166, v50, s[2:3]
	global_load_dwordx4 v[82:85], v[50:51], off offset:16
	global_load_dwordx4 v[90:93], v[50:51], off
	global_load_dwordx4 v[86:89], v[50:51], off offset:80
	global_load_dwordx4 v[94:97], v[50:51], off offset:64
.LBB0_1345:
	s_nop 0
	s_nop 0
	ds_read_b128 v[50:53], v178 offset:33792
	ds_read_b128 v[66:69], v178 offset:33808
	s_nop 0
	s_nop 0
	s_waitcnt lgkmcnt(1)
	v_mfma_f32_32x32x16_bf16 v[50:65], v[158:161], v[50:53], 0
	s_cmpk_lg_i32 s27, 0x80
	s_cselect_b64 vcc, -1, 0
	v_cndmask_b32_e32 v182, v246, v48, vcc
	v_cndmask_b32_e32 v48, v246, v49, vcc
	v_cndmask_b32_e32 v49, v246, v46, vcc
	v_cndmask_b32_e32 v46, v246, v47, vcc
	v_cndmask_b32_e32 v47, v246, v44, vcc
	s_waitcnt lgkmcnt(0)
	v_mfma_f32_32x32x16_bf16 v[50:65], v[154:157], v[66:69], v[50:65]
	ds_read_b128 v[66:69], v178 offset:33824
	v_cndmask_b32_e32 v44, v246, v45, vcc
	v_cndmask_b32_e32 v45, v246, v42, vcc
	v_max_f32_e32 v42, v35, v35
	v_max_f32_e32 v70, v34, v34
	v_max_f32_e32 v42, v70, v42
	ds_read_b128 v[70:73], v178 offset:33840
	s_waitcnt lgkmcnt(1)
	v_mfma_f32_32x32x16_bf16 v[50:65], v[150:153], v[66:69], v[50:65]
	v_max3_f32 v42, v42, v36, v37
	v_max3_f32 v42, v42, v38, v39
	v_cndmask_b32_e32 v43, v246, v43, vcc
	v_max3_f32 v42, v42, v40, v41
	v_max3_f32 v42, v42, v45, v43
	v_max3_f32 v42, v42, v47, v44
	v_max3_f32 v42, v42, v49, v46
	s_waitcnt lgkmcnt(0)
	v_mfma_f32_32x32x16_bf16 v[50:65], v[146:149], v[70:73], v[50:65]
	v_max3_f32 v42, v42, v182, v48
	ds_bpermute_b32 v183, v179, v42
	ds_read_b128 v[66:69], v178 offset:33920
	ds_read_b128 v[70:73], v178 offset:33936
	s_waitcnt lgkmcnt(1)
	v_mfma_f32_32x32x16_bf16 v[50:65], v[142:145], v[66:69], v[50:65]
	s_waitcnt lgkmcnt(0)
	v_mfma_f32_32x32x16_bf16 v[50:65], v[138:141], v[70:73], v[50:65]
	ds_read_b128 v[66:69], v178 offset:33952
	ds_read_b128 v[70:73], v178 offset:33968
	s_waitcnt lgkmcnt(1)
	v_mfma_f32_32x32x16_bf16 v[50:65], v[134:137], v[66:69], v[50:65]
	s_waitcnt lgkmcnt(0)
	v_mfma_f32_32x32x16_bf16 v[50:65], v[130:133], v[70:73], v[50:65]
	ds_read_b128 v[66:69], v178 offset:34048
	ds_read_b128 v[70:73], v178 offset:34064
	s_waitcnt lgkmcnt(1)
	v_mfma_f32_32x32x16_bf16 v[50:65], v[126:129], v[66:69], v[50:65]
	s_waitcnt lgkmcnt(0)
	v_mfma_f32_32x32x16_bf16 v[50:65], v[122:125], v[70:73], v[50:65]
	ds_read_b128 v[66:69], v178 offset:34080
	ds_read_b128 v[70:73], v178 offset:34096
	s_waitcnt lgkmcnt(1)
	v_mfma_f32_32x32x16_bf16 v[50:65], v[118:121], v[66:69], v[50:65]
	s_waitcnt lgkmcnt(0)
	v_mfma_f32_32x32x16_bf16 v[50:65], v[114:117], v[70:73], v[50:65]
	ds_read_b128 v[66:69], v178 offset:34176
	ds_read_b128 v[70:73], v178 offset:34192
	s_waitcnt lgkmcnt(1)
	v_mfma_f32_32x32x16_bf16 v[50:65], v[110:113], v[66:69], v[50:65]
	s_waitcnt lgkmcnt(0)
	v_mfma_f32_32x32x16_bf16 v[50:65], v[106:109], v[70:73], v[50:65]
	ds_read_b128 v[66:69], v178 offset:34208
	ds_read_b128 v[70:73], v178 offset:34224
	s_waitcnt lgkmcnt(1)
	v_mfma_f32_32x32x16_bf16 v[50:65], v[102:105], v[66:69], v[50:65]
	s_waitcnt lgkmcnt(0)
	v_mfma_f32_32x32x16_bf16 v[50:65], v[98:101], v[70:73], v[50:65]
	ds_read_b128 v[66:69], v178 offset:50688
	v_cndmask_b32_e64 v70, 0, 1, s[56:57]
	v_cmp_ne_u32_e64 s[2:3], 1, v70
	s_andn2_b64 vcc, exec, s[56:57]
	s_waitcnt lgkmcnt(0)
	v_mfma_f32_32x32x16_bf16 v[66:81], v[158:161], v[66:69], 0
	s_cbranch_vccnz .LBB0_1347
	global_load_dwordx4 v[158:161], v[190:191], off offset:-4096
; #define LAS __attribute__((address_space(3)))
; #define MFMA32(a, b, c) __builtin_amdgcn_mfma_f32_32x32x16_bf16((a), (b), (c), 0, 0, 0)
; DEVI void sample_attn_fused(int wv, LAS unsigned char* lds, int l, int bh) {
;     ...
;         {
;             f32x16 v;
; #pragma unroll
;             for (int r = 0; r < 16; ++r) v[r] = 0.f;
; #pragma unroll
;             for (int ks = 0; ks < 16; ++ks) {
;                 v = MFMA32(cf[ks], *(const LAS bf16x8*)(wvl + 32 * FS_PITCH + 2 * FS_KO(ks)), v);
;                 if (more) cf[ks] = *(const bf16x8*)(ncp + FS_KO(ks));
;                 if ((ks & 3) == 3) __builtin_amdgcn_sched_barrier(0);
;             }
;             o1 = MFMA32(pk_regs(v, 0, 1.f), pb0, o1); o1 = MFMA32(pk_regs(v, 1, 1.f), pb1, o1);
.LBB0_1347:
	ds_read_b128 v[184:187], v178 offset:50704
	s_and_b64 vcc, exec, s[2:3]
	s_waitcnt lgkmcnt(0)
	v_mfma_f32_32x32x16_bf16 v[66:81], v[154:157], v[184:187], v[66:81]
	s_cbranch_vccnz .LBB0_1349
	global_load_dwordx4 v[154:157], v[190:191], off offset:-3072
.LBB0_1349:
	ds_read_b128 v[184:187], v178 offset:50720
	s_and_b64 vcc, exec, s[2:3]
	s_waitcnt lgkmcnt(0)
	v_mfma_f32_32x32x16_bf16 v[66:81], v[150:153], v[184:187], v[66:81]
	s_cbranch_vccnz .LBB0_1351
	global_load_dwordx4 v[150:153], v[190:191], off offset:-2048
.LBB0_1351:
	ds_read_b128 v[184:187], v178 offset:50736
	s_and_b64 vcc, exec, s[2:3]
	s_waitcnt lgkmcnt(0)
	v_mfma_f32_32x32x16_bf16 v[66:81], v[146:149], v[184:187], v[66:81]
	s_cbranch_vccnz .LBB0_1353
	global_load_dwordx4 v[146:149], v[190:191], off offset:-1024
.LBB0_1353:
	ds_read_b128 v[184:187], v178 offset:50816
	s_and_b64 vcc, exec, s[2:3]
	s_waitcnt lgkmcnt(0)
	v_mfma_f32_32x32x16_bf16 v[66:81], v[142:145], v[184:187], v[66:81]
	s_cbranch_vccnz .LBB0_1355
	global_load_dwordx4 v[142:145], v[190:191], off
.LBB0_1355:
	ds_read_b128 v[184:187], v178 offset:50832
	s_and_b64 vcc, exec, s[2:3]
	s_waitcnt lgkmcnt(0)
	v_mfma_f32_32x32x16_bf16 v[66:81], v[138:141], v[184:187], v[66:81]
	s_cbranch_vccnz .LBB0_1357
	global_load_dwordx4 v[138:141], v[190:191], off offset:1024
.LBB0_1357:
	ds_read_b128 v[184:187], v178 offset:50848
	s_and_b64 vcc, exec, s[2:3]
	s_waitcnt lgkmcnt(0)
	v_mfma_f32_32x32x16_bf16 v[66:81], v[134:137], v[184:187], v[66:81]
	s_cbranch_vccnz .LBB0_1359
	global_load_dwordx4 v[134:137], v[190:191], off offset:2048
.LBB0_1359:
	ds_read_b128 v[184:187], v178 offset:50864
	s_and_b64 vcc, exec, s[2:3]
	s_waitcnt lgkmcnt(0)
	v_mfma_f32_32x32x16_bf16 v[66:81], v[130:133], v[184:187], v[66:81]
	s_cbranch_vccnz .LBB0_1361
	global_load_dwordx4 v[130:133], v[190:191], off offset:3072
.LBB0_1361:
	ds_read_b128 v[184:187], v178 offset:50944
	s_and_b64 vcc, exec, s[2:3]
	s_waitcnt lgkmcnt(0)
	v_mfma_f32_32x32x16_bf16 v[66:81], v[126:129], v[184:187], v[66:81]
	s_cbranch_vccnz .LBB0_1363
	global_load_dwordx4 v[126:129], v[192:193], off offset:-4096
.LBB0_1363:
	ds_read_b128 v[184:187], v178 offset:50960
	s_and_b64 vcc, exec, s[2:3]
	s_waitcnt lgkmcnt(0)
	v_mfma_f32_32x32x16_bf16 v[66:81], v[122:125], v[184:187], v[66:81]
	s_cbranch_vccnz .LBB0_1365
	global_load_dwordx4 v[122:125], v[192:193], off offset:-3072
.LBB0_1365:
	ds_read_b128 v[184:187], v178 offset:50976
	s_and_b64 vcc, exec, s[2:3]
	s_waitcnt lgkmcnt(0)
	v_mfma_f32_32x32x16_bf16 v[66:81], v[118:121], v[184:187], v[66:81]
	s_cbranch_vccnz .LBB0_1367
	global_load_dwordx4 v[118:121], v[192:193], off offset:-2048
.LBB0_1367:
	ds_read_b128 v[184:187], v178 offset:50992
	s_and_b64 vcc, exec, s[2:3]
	s_waitcnt lgkmcnt(0)
	v_mfma_f32_32x32x16_bf16 v[66:81], v[114:117], v[184:187], v[66:81]
	s_cbranch_vccnz .LBB0_1369
	global_load_dwordx4 v[114:117], v[192:193], off offset:-1024
.LBB0_1369:
	ds_read_b128 v[184:187], v178 offset:51072
	s_and_b64 vcc, exec, s[2:3]
	s_waitcnt lgkmcnt(0)
	v_mfma_f32_32x32x16_bf16 v[66:81], v[110:113], v[184:187], v[66:81]
	s_cbranch_vccnz .LBB0_1371
	global_load_dwordx4 v[110:113], v[192:193], off
.LBB0_1371:
	ds_read_b128 v[184:187], v178 offset:51088
	s_and_b64 vcc, exec, s[2:3]
	s_waitcnt lgkmcnt(0)
	v_mfma_f32_32x32x16_bf16 v[66:81], v[106:109], v[184:187], v[66:81]
	s_cbranch_vccnz .LBB0_1373
	global_load_dwordx4 v[106:109], v[192:193], off offset:1024
.LBB0_1373:
	ds_read_b128 v[184:187], v178 offset:51104
	s_and_b64 vcc, exec, s[2:3]
	s_waitcnt lgkmcnt(0)
	v_mfma_f32_32x32x16_bf16 v[66:81], v[102:105], v[184:187], v[66:81]
	s_cbranch_vccnz .LBB0_1375
	global_load_dwordx4 v[102:105], v[192:193], off offset:2048
.LBB0_1375:
	ds_read_b128 v[184:187], v178 offset:51120
	s_and_b64 vcc, exec, s[2:3]
	s_waitcnt lgkmcnt(0)
	v_mfma_f32_32x32x16_bf16 v[66:81], v[98:101], v[184:187], v[66:81]
	s_cbranch_vccnz .LBB0_1377
	global_load_dwordx4 v[98:101], v[192:193], off offset:3072
